# s=3 phase: blocks 256..511 run their G3/G2 tiles before their dn_pre units so a CU's two blocks overlap bandwidth-bound tiles with latency-bound dn_pre
# speedup vs baseline: 1.0084x; 1.0029x over previous
.LBB0_345:
	s_and_b64 vcc, exec, s[36:37]
	s_cbranch_vccz .LBB0_564
	v_readlane_b32 s2, v253, 13
	v_readlane_b32 s3, v253, 14
	s_andn2_b64 vcc, exec, s[2:3]
	v_readlane_b32 s2, v250, 0
	s_mov_b32 s40, s2
	s_mov_b32 s100, 0
	s_cbranch_vccnz .LBB0_347
	s_cmpk_lt_u32 s2, 0x100
	s_cbranch_scc1 .LBB0_397
	s_mov_b32 s100, 1
.LBB0_347:
	s_cmp_eq_u32 s100, 2
	s_cbranch_scc0 .Lmy_s3_norm
	s_mov_b32 s100, 0
	s_branch .LBB0_564

.LBB0_564:
	s_cmp_eq_u32 s100, 1
	s_cbranch_scc0 .Lmy_s3_end
	s_mov_b32 s100, 2
	v_readlane_b32 s2, v250, 0
	s_nop 0
	s_mov_b32 s40, s2
	s_branch .LBB0_397
